# attention V path: coalesced V row loads sharing K addresses, row-major 8-key-group V image in LDS via 8 ds_write_b64, PV operand via ds_read_b64_tr_b16 (replaces 32 ds_write_b16 per thread and uncoale
# speedup vs baseline: 1.0006x; 1.0006x over previous
.LBB0_469:
	s_add_i32 s31, s24, 0xfffffd60
	v_mov_b32_e32 v51, v201
	s_cmpk_gt_u32 s31, 0xbff
	s_cbranch_scc1 .LBB0_508
	s_and_b32 s2, s31, 0xffff
	s_mul_i32 s2, s2, 0xaaab
	s_lshr_b32 s4, s2, 23
	s_mulk_i32 s4, 0xc0
	s_sub_i32 s4, s31, s4
	s_and_b32 s6, s4, 63
	s_lshr_b32 s4, s4, 5
	s_and_b32 s5, s4, 6
	s_lshr_b32 s4, 64, s5
	s_add_i32 s4, s4, -1
	s_and_b32 s4, s4, s6
	s_lshl_b32 s8, s4, 7
	s_xor_b32 s7, s5, 6
	s_add_i32 s10, s8, 0xffffff80
	s_lshr_b32 s4, s2, 12
	v_lshlrev_b32_e32 v0, 3, v51
	v_ashrrev_i32_e32 v90, 3, v51
	s_lshr_b32 s7, s6, s7
	s_and_b32 s4, s4, 0xe000
	s_lshr_b32 s2, s2, 17
	v_and_b32_e32 v36, 56, v0
	v_add_u32_e32 v0, s10, v90
	v_mov_b32 v4, 0
	s_or_b32 s4, s7, s4
	v_mov_b32_e32 v5, v4
	s_and_b32 s9, s2, 0xc0
	v_cmp_lt_i32_e32 vcc, -1, v0
	v_lshlrev_b32_e32 v78, 1, v36
	v_mov_b64_e32 v[2:3], v[4:5]
	v_mov_b64_e32 v[18:19], v[4:5]
	v_mov_b64_e32 v[20:21], v[4:5]
	s_and_saveexec_b64 s[6:7], vcc
	s_cbranch_execz .LBB0_472
	v_readlane_b32 s12, v254, 1
	v_lshlrev_b32_e32 v0, s5, v0
	v_readlane_b32 s13, v254, 2
	v_add_u32_e32 v0, s4, v0
	s_movk_i32 s2, 0x1400
	v_mov_b64_e32 v[2:3], s[12:13]
	v_mad_i64_i32 v[2:3], s[12:13], v0, s2, v[2:3]
	s_lshl_b32 s2, s9, 1
	v_lshl_add_u64 v[2:3], v[2:3], 0, s[2:3]
	v_mov_b32_e32 v79, v1
	v_lshl_add_u64 v[2:3], v[2:3], 0, v[78:79]
	global_load_dwordx4 v[18:21], v[2:3], off offset:1536
	s_nop 0
	global_load_dwordx4 v[2:5], v[2:3], off offset:1024
.LBB0_472:
	s_or_b64 exec, exec, s[6:7]
	v_add_u32_e32 v52, 0x200, v51
	v_ashrrev_i32_e32 v91, 3, v52
	v_add_u32_e32 v0, s10, v91
	v_mov_b32 v8, 0
	v_cmp_lt_i32_e32 vcc, -1, v0
	v_mov_b32_e32 v9, v8
	v_mov_b64_e32 v[6:7], v[8:9]
	v_mov_b64_e32 v[22:23], v[8:9]
	v_mov_b64_e32 v[24:25], v[8:9]
	s_and_saveexec_b64 s[6:7], vcc
	s_cbranch_execz .LBB0_474
	v_readlane_b32 s12, v254, 1
	v_lshlrev_b32_e32 v0, s5, v0
	v_readlane_b32 s13, v254, 2
	v_add_u32_e32 v0, s4, v0
	s_movk_i32 s2, 0x1400
	v_mov_b64_e32 v[6:7], s[12:13]
	v_mad_i64_i32 v[6:7], s[12:13], v0, s2, v[6:7]
	s_lshl_b32 s2, s9, 1
	v_lshl_add_u64 v[6:7], v[6:7], 0, s[2:3]
	v_mov_b32_e32 v79, v1
	v_lshl_add_u64 v[6:7], v[6:7], 0, v[78:79]
	global_load_dwordx4 v[22:25], v[6:7], off offset:1536
	s_nop 0
	global_load_dwordx4 v[6:9], v[6:7], off offset:1024
.LBB0_474:
	s_or_b64 exec, exec, s[6:7]
	v_add_u32_e32 v0, 0x400, v51
	v_ashrrev_i32_e32 v92, 3, v0
	v_add_u32_e32 v14, s10, v92
	v_mov_b32 v12, 0
	v_cmp_lt_i32_e32 vcc, -1, v14
	v_mov_b32_e32 v13, v12
	v_mov_b64_e32 v[10:11], v[12:13]
	v_mov_b64_e32 v[26:27], v[12:13]
	v_mov_b64_e32 v[28:29], v[12:13]
	s_and_saveexec_b64 s[6:7], vcc
	s_cbranch_execz .LBB0_476
	v_readlane_b32 s12, v254, 1
	v_lshlrev_b32_e32 v10, s5, v14
	v_readlane_b32 s13, v254, 2
	v_add_u32_e32 v12, s4, v10
	s_movk_i32 s2, 0x1400
	v_mov_b64_e32 v[10:11], s[12:13]
	v_mad_i64_i32 v[10:11], s[12:13], v12, s2, v[10:11]
	s_lshl_b32 s2, s9, 1
	v_lshl_add_u64 v[10:11], v[10:11], 0, s[2:3]
	v_mov_b32_e32 v79, v1
	v_lshl_add_u64 v[10:11], v[10:11], 0, v[78:79]
	global_load_dwordx4 v[26:29], v[10:11], off offset:1536
	s_nop 0
	global_load_dwordx4 v[10:13], v[10:11], off offset:1024
.LBB0_476:
	s_or_b64 exec, exec, s[6:7]
	v_add_u32_e32 v54, 0x600, v51
	v_ashrrev_i32_e32 v93, 3, v54
	v_add_u32_e32 v106, s10, v93
	v_mov_b32 v16, 0
	v_cmp_lt_i32_e32 vcc, -1, v106
	v_mov_b32_e32 v17, v16
	v_mov_b64_e32 v[14:15], v[16:17]
	v_mov_b64_e32 v[30:31], v[16:17]
	v_mov_b64_e32 v[32:33], v[16:17]
	s_and_saveexec_b64 s[6:7], vcc
	s_cbranch_execz .LBB0_478
	v_readlane_b32 s12, v254, 1
	v_lshlrev_b32_e32 v14, s5, v106
	v_readlane_b32 s13, v254, 2
	v_add_u32_e32 v16, s4, v14
	s_movk_i32 s2, 0x1400
	v_mov_b64_e32 v[14:15], s[12:13]
	v_mad_i64_i32 v[14:15], s[12:13], v16, s2, v[14:15]
	s_lshl_b32 s2, s9, 1
	v_lshl_add_u64 v[14:15], v[14:15], 0, s[2:3]
	v_mov_b32_e32 v79, v1
	v_lshl_add_u64 v[14:15], v[14:15], 0, v[78:79]
	global_load_dwordx4 v[30:33], v[14:15], off offset:1536
	s_nop 0
	global_load_dwordx4 v[14:17], v[14:15], off offset:1024
.LBB0_478:
	s_or_b64 exec, exec, s[6:7]
	v_and_b32_e32 v94, 0xff, v51
	s_lshl_b32 s2, s9, 1
	v_ashrrev_i32_e32 v53, 5, v51
	v_and_b32_e32 v80, -8, v53
	v_ashrrev_i32_e32 v55, 5, v52
	v_and_b32_e32 v82, -8, v55
	v_ashrrev_i32_e32 v56, 5, v0
	v_and_b32_e32 v84, -8, v56
	v_ashrrev_i32_e32 v57, 5, v54
	v_and_b32_e32 v86, -8, v57
	v_ashrrev_i32_e32 v87, 31, v86
	v_and_b32_e32 v35, 15, v51
	v_ashrrev_i32_e32 v50, 2, v51
	v_or_b32_e32 v0, s8, v35
	v_and_b32_e32 v34, -16, v50
	v_add_u32_e32 v38, v0, v34
	v_ashrrev_i32_e32 v39, 31, v38
	v_lshlrev_b64 v[38:39], s5, v[38:39]
	s_mov_b32 s5, s3
	v_lshl_add_u64 v[38:39], v[38:39], 0, s[4:5]
	v_readlane_b32 s4, v254, 1
	v_readlane_b32 s5, v254, 2
	s_movk_i32 s6, 0x1400
	v_bfe_u32 v58, v51, 4, 2
	v_mov_b64_e32 v[40:41], s[4:5]
	v_mad_u64_u32 v[40:41], s[4:5], v38, s6, v[40:41]
	v_ashrrev_i32_e32 v37, 6, v51
	v_cmp_eq_u32_e64 s[4:5], 0, v58
	v_mad_i32_i24 v41, v39, s6, v41
	v_lshrrev_b32_e32 v0, 1, v51
	v_bfi_b32 v95, -16, v50, v51
	v_lshlrev_b32_e32 v59, 4, v37
	v_writelane_b32 v254, s4, 24
	v_lshrrev_b32_e32 v51, 6, v51
	v_lshrrev_b32_e32 v52, 6, v52
	v_lshl_add_u64 v[38:39], v[40:41], 0, s[2:3]
	v_or_b32_e32 v96, v59, v35
	v_writelane_b32 v254, s5, 25
	s_movk_i32 s2, 0x90
	v_and_b32_e32 v62, 12, v51
	s_mov_b32 s4, 0xfffffe0
	v_and_b32_e32 v52, 12, v52
	v_and_b32_e32 v34, 24, v0
	v_and_or_b32 v51, v53, s4, v62
	v_and_or_b32 v52, v55, s4, v52
	v_and_or_b32 v53, v56, s4, v62
	v_lshrrev_b32_e32 v54, 6, v54
	v_mul_lo_u32 v55, v96, s2
	v_lshlrev_b32_e32 v56, 4, v58
	v_lshlrev_b32_e32 v0, 1, v34
	v_and_b32_e32 v54, 12, v54
	v_add3_u32 v97, 0, v55, v56
	v_add_u32_e32 v55, 1, v37
	v_lshl_add_u64 v[38:39], v[38:39], 0, v[0:1]
	v_and_or_b32 v54, v57, s4, v54
	v_lshlrev_b32_e32 v57, 4, v55
	global_load_dwordx4 v[42:45], v[38:39], off offset:576
	global_load_dwordx4 v[46:49], v[38:39], off offset:512
	v_lshl_add_u32 v38, v36, 1, 0
	v_lshlrev_b32_e32 v36, 3, v58
	v_lshlrev_b32_e32 v60, 2, v58
	v_or_b32_e32 v58, v57, v35
	v_mul_lo_u32 v58, v58, s2
	v_add3_u32 v98, 0, v58, v56
	v_add_u32_e32 v58, 2, v37
	v_lshlrev_b32_e32 v62, 4, v58
	v_or_b32_e32 v63, v62, v35
	v_mul_lo_u32 v63, v63, s2
	v_add3_u32 v99, 0, v63, v56
	v_add_u32_e32 v63, 3, v37
	v_lshlrev_b32_e32 v64, 4, v63
	v_or_b32_e32 v65, v64, v35
	v_mul_lo_u32 v65, v65, s2
	v_add3_u32 v100, 0, v65, v56
	v_add_u32_e32 v65, 4, v37
	v_lshlrev_b32_e32 v66, 4, v65
	v_or_b32_e32 v67, v66, v35
	v_mul_lo_u32 v67, v67, s2
	v_add3_u32 v101, 0, v67, v56
	v_add_u32_e32 v67, 5, v37
	v_lshlrev_b32_e32 v68, 4, v67
	v_or_b32_e32 v69, v68, v35
	v_mul_lo_u32 v69, v69, s2
	v_add3_u32 v102, 0, v69, v56
	v_add_u32_e32 v69, 6, v37
	v_lshlrev_b32_e32 v70, 4, v69
	v_or_b32_e32 v71, v70, v35
	v_mul_lo_u32 v71, v71, s2
	v_add3_u32 v103, 0, v71, v56
	v_add_u32_e32 v71, 7, v37
	v_lshlrev_b32_e32 v72, 4, v71
	v_or_b32_e32 v73, v72, v35
	v_mul_lo_u32 v73, v73, s2
	v_add3_u32 v104, 0, v73, v56
	v_add_u32_e32 v73, 8, v37
	v_lshlrev_b32_e32 v74, 4, v73
	v_or_b32_e32 v75, v74, v35
	v_mul_lo_u32 v75, v75, s2
	v_add_u32_e32 v61, 0x80, v96
	v_add3_u32 v105, 0, v75, v56
	v_or_b32_e32 v56, v60, v59
	v_mul_lo_u32 v39, v90, s2
	v_mul_lo_u32 v40, v91, s2
	v_mul_lo_u32 v41, v92, s2
	v_mul_lo_u32 v50, v93, s2
	v_sub_u32_e32 v59, v61, v56
	s_movk_i32 s18, 0x81
	s_movk_i32 s2, 0x100
	v_cmp_gt_u32_e32 vcc, s18, v59
	v_cmp_gt_i32_e64 s[4:5], s2, v56
	s_and_b64 s[4:5], s[4:5], vcc
	s_movk_i32 s28, 0x7f
	v_writelane_b32 v254, s4, 9
	v_or_b32_e32 v59, 1, v56
	v_sub_u32_e32 v75, v61, v59
	v_writelane_b32 v254, s5, 10
	v_cmp_lt_i32_e64 s[4:5], s28, v56
	v_cmp_gt_u32_e32 vcc, s18, v75
	s_movk_i32 s16, 0x7e
	v_writelane_b32 v253, s4, 59
	s_movk_i32 s29, 0x230
	v_mad_u32_u24 v35, v35, s29, 0
	v_writelane_b32 v253, s5, 60
	v_cmp_gt_i32_e64 s[4:5], s2, v59
	s_and_b64 s[4:5], s[4:5], vcc
	v_or_b32_e32 v59, 2, v56
	v_writelane_b32 v254, s4, 20
	v_sub_u32_e32 v75, v61, v59
	v_cmp_gt_u32_e32 vcc, s18, v75
	v_writelane_b32 v254, s5, 21
	v_cmp_lt_i32_e64 s[4:5], s16, v56
	v_or_b32_e32 v56, 3, v56
	v_lshlrev_b32_e32 v37, 5, v37
	v_writelane_b32 v254, s4, 22
	v_lshlrev_b32_e32 v55, 5, v55
	v_add3_u32 v107, v35, v37, v36
	v_writelane_b32 v254, s5, 23
	v_cmp_gt_i32_e64 s[4:5], s2, v59
	s_and_b64 s[4:5], s[4:5], vcc
	v_add3_u32 v106, v35, v55, v36
	v_writelane_b32 v254, s4, 26
	v_lshl_add_u32 v0, v94, 1, 0
	v_mul_lo_u32 v51, v51, s29
	v_writelane_b32 v254, s5, 27
	v_cmp_lt_i32_e64 s[4:5], s28, v59
	v_sub_u32_e32 v59, v61, v56
	v_cmp_gt_u32_e32 vcc, s18, v59
	v_writelane_b32 v254, s4, 28
	v_mul_lo_u32 v52, v52, s29
	v_mul_lo_u32 v53, v53, s29
	v_writelane_b32 v254, s5, 29
	v_cmp_gt_i32_e64 s[4:5], s2, v56
	s_and_b64 s[4:5], s[4:5], vcc
	v_mul_lo_u32 v54, v54, s29
	v_writelane_b32 v254, s4, 30
	v_add_u32_e32 v124, v38, v39
	v_add_u32_e32 v125, v38, v40
	v_writelane_b32 v254, s5, 31
	v_cmp_lt_i32_e64 s[4:5], s28, v56
	v_or_b32_e32 v56, v57, v60
	v_sub_u32_e32 v57, v61, v56
	v_writelane_b32 v254, s4, 32
	v_cmp_gt_u32_e32 vcc, s18, v57
	v_or_b32_e32 v57, 1, v56
	v_writelane_b32 v254, s5, 33
	v_cmp_gt_i32_e64 s[4:5], s2, v56
	s_and_b64 s[4:5], s[4:5], vcc
	v_sub_u32_e32 v59, v61, v57
	v_writelane_b32 v254, s4, 34
	v_cmp_gt_u32_e32 vcc, s18, v59
	v_add_u32_e32 v126, v38, v41
	v_writelane_b32 v254, s5, 35
	v_cmp_lt_i32_e64 s[4:5], s28, v56
	v_add_u32_e32 v127, v38, v50
	v_add_u32_e32 v128, v0, v51
	v_writelane_b32 v254, s4, 36
	v_add_u32_e32 v129, v0, v52
	v_add_u32_e32 v130, v0, v53
	v_writelane_b32 v254, s5, 37
	v_cmp_gt_i32_e64 s[4:5], s2, v57
	s_and_b64 s[4:5], s[4:5], vcc
	v_or_b32_e32 v57, 2, v56
	v_writelane_b32 v254, s4, 38
	v_sub_u32_e32 v59, v61, v57
	v_cmp_gt_u32_e32 vcc, s18, v59
	v_writelane_b32 v254, s5, 39
	v_cmp_lt_i32_e64 s[4:5], s16, v56
	v_or_b32_e32 v56, 3, v56
	v_add_u32_e32 v131, v0, v54
	v_writelane_b32 v254, s4, 40
	v_lshlrev_b32_e32 v0, 1, v34
	v_lshlrev_b32_e32 v88, 1, v36
	v_writelane_b32 v254, s5, 41
	v_cmp_gt_i32_e64 s[4:5], s2, v57
	s_and_b64 s[4:5], s[4:5], vcc
	s_waitcnt vmcnt(1)
	v_mov_b64_e32 v[38:39], v[42:43]
	v_writelane_b32 v254, s4, 42
	v_ashrrev_i32_e32 v81, 31, v80
	v_ashrrev_i32_e32 v83, 31, v82
	v_writelane_b32 v254, s5, 43
	v_cmp_lt_i32_e64 s[4:5], s28, v57
	v_sub_u32_e32 v57, v61, v56
	v_cmp_gt_u32_e32 vcc, s18, v57
	v_writelane_b32 v254, s4, 44
	v_ashrrev_i32_e32 v85, 31, v84
	v_mov_b64_e32 v[40:41], v[44:45]
	v_writelane_b32 v254, s5, 45
	v_cmp_gt_i32_e64 s[4:5], s2, v56
	s_and_b64 s[4:5], s[4:5], vcc
	s_nop 0
	v_writelane_b32 v254, s4, 46
	s_nop 1
	v_writelane_b32 v254, s5, 47
	v_cmp_lt_i32_e64 s[4:5], s28, v56
	v_or_b32_e32 v56, v62, v60
	v_sub_u32_e32 v57, v61, v56
	v_writelane_b32 v254, s4, 48
	v_cmp_gt_u32_e32 vcc, s18, v57
	v_or_b32_e32 v57, 1, v56
	v_writelane_b32 v254, s5, 49
	v_cmp_gt_i32_e64 s[4:5], s2, v56
	s_and_b64 s[4:5], s[4:5], vcc
	v_sub_u32_e32 v59, v61, v57
	v_writelane_b32 v254, s4, 50
	v_cmp_gt_u32_e32 vcc, s18, v59
	s_nop 0
	v_writelane_b32 v254, s5, 51
	v_cmp_lt_i32_e64 s[4:5], s28, v56
	s_nop 1
	v_writelane_b32 v254, s4, 52
	s_nop 1
	v_writelane_b32 v254, s5, 53
	v_cmp_gt_i32_e64 s[4:5], s2, v57
	s_and_b64 s[4:5], s[4:5], vcc
	v_or_b32_e32 v57, 2, v56
	v_writelane_b32 v254, s4, 54
	v_sub_u32_e32 v59, v61, v57
	v_cmp_gt_u32_e32 vcc, s18, v59
	v_writelane_b32 v254, s5, 55
	v_cmp_lt_i32_e64 s[4:5], s16, v56
	v_or_b32_e32 v56, 3, v56
	s_nop 0
	v_writelane_b32 v254, s4, 56
	s_nop 1
	v_writelane_b32 v254, s5, 57
	v_cmp_gt_i32_e64 s[4:5], s2, v57
	s_and_b64 s[4:5], s[4:5], vcc
	s_nop 0
	v_writelane_b32 v254, s4, 58
	s_nop 1
	v_writelane_b32 v254, s5, 59
	v_cmp_lt_i32_e64 s[4:5], s28, v57
	v_sub_u32_e32 v57, v61, v56
	v_cmp_gt_u32_e32 vcc, s18, v57
	v_writelane_b32 v254, s4, 60
	s_nop 1
	v_writelane_b32 v254, s5, 61
	v_cmp_gt_i32_e64 s[4:5], s2, v56
	s_and_b64 s[4:5], s[4:5], vcc
	s_nop 0
	v_writelane_b32 v254, s4, 62
	s_nop 1
	v_writelane_b32 v254, s5, 63
	v_cmp_lt_i32_e64 s[4:5], s28, v56
	v_or_b32_e32 v56, v64, v60
	v_sub_u32_e32 v57, v61, v56
	v_writelane_b32 v255, s4, 0
	v_cmp_gt_u32_e32 vcc, s18, v57
	v_or_b32_e32 v57, 1, v56
	v_writelane_b32 v255, s5, 1
	v_cmp_gt_i32_e64 s[4:5], s2, v56
	s_and_b64 s[4:5], s[4:5], vcc
	v_sub_u32_e32 v59, v61, v57
	v_writelane_b32 v255, s4, 2
	v_cmp_gt_u32_e32 vcc, s18, v59
	s_nop 0
	v_writelane_b32 v255, s5, 3
	v_cmp_lt_i32_e64 s[4:5], s28, v56
	s_nop 1
	v_writelane_b32 v255, s4, 4
	s_nop 1
	v_writelane_b32 v255, s5, 5
	v_cmp_gt_i32_e64 s[4:5], s2, v57
	s_and_b64 s[4:5], s[4:5], vcc
	v_or_b32_e32 v57, 2, v56
	v_writelane_b32 v255, s4, 6
	v_sub_u32_e32 v59, v61, v57
	v_cmp_gt_u32_e32 vcc, s18, v59
	v_writelane_b32 v255, s5, 7
	v_cmp_lt_i32_e64 s[4:5], s16, v56
	v_or_b32_e32 v56, 3, v56
	s_nop 0
	v_writelane_b32 v255, s4, 8
	s_nop 1
	v_writelane_b32 v255, s5, 9
	v_cmp_gt_i32_e64 s[4:5], s2, v57
	s_and_b64 s[4:5], s[4:5], vcc
	s_nop 0
	v_writelane_b32 v255, s4, 10
	s_nop 1
	v_writelane_b32 v255, s5, 11
	v_cmp_lt_i32_e64 s[4:5], s28, v57
	v_sub_u32_e32 v57, v61, v56
	v_cmp_gt_u32_e32 vcc, s18, v57
	v_writelane_b32 v255, s4, 12
	s_nop 1
	v_writelane_b32 v255, s5, 13
	v_cmp_gt_i32_e64 s[4:5], s2, v56
	s_and_b64 s[4:5], s[4:5], vcc
	s_nop 0
	v_writelane_b32 v255, s4, 14
	s_nop 1
	v_writelane_b32 v255, s5, 15
	v_cmp_lt_i32_e64 s[4:5], s28, v56
	v_or_b32_e32 v56, v66, v60
	v_sub_u32_e32 v57, v61, v56
	v_writelane_b32 v255, s4, 16
	v_cmp_gt_u32_e32 vcc, s18, v57
	v_or_b32_e32 v57, 1, v56
	v_writelane_b32 v255, s5, 17
	v_cmp_gt_i32_e64 s[4:5], s2, v56
	s_and_b64 s[40:41], s[4:5], vcc
	v_sub_u32_e32 v59, v61, v57
	v_cmp_gt_i32_e64 s[4:5], s2, v57
	v_or_b32_e32 v57, 2, v56
	v_cmp_gt_u32_e32 vcc, s18, v59
	v_sub_u32_e32 v59, v61, v57
	v_cmp_lt_i32_e64 s[74:75], s28, v56
	s_and_b64 s[52:53], s[4:5], vcc
	v_cmp_lt_i32_e64 s[76:77], s16, v56
	v_cmp_gt_u32_e32 vcc, s18, v59
	v_cmp_gt_i32_e64 s[4:5], s2, v57
	v_or_b32_e32 v56, 3, v56
	s_and_b64 s[20:21], s[4:5], vcc
	v_cmp_lt_i32_e64 s[78:79], s28, v57
	v_sub_u32_e32 v57, v61, v56
	v_cmp_gt_i32_e64 s[4:5], s2, v56
	v_cmp_lt_i32_e64 s[80:81], s28, v56
	v_or_b32_e32 v56, v68, v60
	v_cmp_gt_u32_e32 vcc, s18, v57
	v_sub_u32_e32 v57, v61, v56
	s_and_b64 s[54:55], s[4:5], vcc
	v_cmp_gt_u32_e32 vcc, s18, v57
	v_cmp_gt_i32_e64 s[4:5], s2, v56
	v_or_b32_e32 v57, 1, v56
	s_and_b64 s[42:43], s[4:5], vcc
	v_sub_u32_e32 v59, v61, v57
	v_cmp_gt_i32_e64 s[4:5], s2, v57
	v_or_b32_e32 v57, 2, v56
	v_cmp_gt_u32_e32 vcc, s18, v59
	v_sub_u32_e32 v59, v61, v57
	v_cmp_lt_i32_e64 s[82:83], s28, v56
	s_and_b64 s[56:57], s[4:5], vcc
	v_cmp_lt_i32_e64 s[84:85], s16, v56
	v_cmp_gt_u32_e32 vcc, s18, v59
	v_cmp_gt_i32_e64 s[4:5], s2, v57
	v_or_b32_e32 v56, 3, v56
	s_and_b64 s[22:23], s[4:5], vcc
	v_cmp_lt_i32_e64 s[86:87], s28, v57
	v_sub_u32_e32 v57, v61, v56
	v_cmp_gt_i32_e64 s[4:5], s2, v56
	v_cmp_lt_i32_e64 s[88:89], s28, v56
	v_or_b32_e32 v56, v70, v60
	v_cmp_gt_u32_e32 vcc, s18, v57
	v_sub_u32_e32 v57, v61, v56
	s_and_b64 s[58:59], s[4:5], vcc
	v_cmp_gt_u32_e32 vcc, s18, v57
	v_cmp_gt_i32_e64 s[4:5], s2, v56
	v_or_b32_e32 v57, 1, v56
	s_and_b64 s[44:45], s[4:5], vcc
	v_sub_u32_e32 v59, v61, v57
	v_cmp_gt_i32_e64 s[4:5], s2, v57
	v_or_b32_e32 v57, 2, v56
	v_cmp_gt_u32_e32 vcc, s18, v59
	v_sub_u32_e32 v59, v61, v57
	v_cmp_lt_i32_e64 s[90:91], s28, v56
	s_and_b64 s[60:61], s[4:5], vcc
	v_cmp_lt_i32_e64 s[92:93], s16, v56
	v_cmp_gt_u32_e32 vcc, s18, v59
	v_cmp_gt_i32_e64 s[4:5], s2, v57
	v_or_b32_e32 v56, 3, v56
	s_and_b64 s[24:25], s[4:5], vcc
	v_cmp_lt_i32_e64 s[94:95], s28, v57
	v_sub_u32_e32 v57, v61, v56
	v_cmp_gt_i32_e64 s[4:5], s2, v56
	v_cmp_lt_i32_e64 s[96:97], s28, v56
	v_or_b32_e32 v56, v72, v60
	v_cmp_gt_u32_e32 vcc, s18, v57
	v_sub_u32_e32 v57, v61, v56
	s_and_b64 s[62:63], s[4:5], vcc
	v_cmp_gt_u32_e32 vcc, s18, v57
	v_or_b32_e32 v57, 1, v56
	v_cmp_gt_i32_e64 s[4:5], s2, v56
	v_sub_u32_e32 v59, v61, v57
	v_cmp_gt_i32_e64 s[6:7], s2, v57
	v_or_b32_e32 v57, 2, v56
	s_and_b64 s[46:47], s[4:5], vcc
	v_cmp_gt_u32_e32 vcc, s18, v59
	v_sub_u32_e32 v59, v61, v57
	v_cmp_lt_i32_e64 s[4:5], s28, v56
	s_and_b64 s[64:65], s[6:7], vcc
	v_cmp_lt_i32_e64 s[6:7], s16, v56
	v_cmp_gt_u32_e32 vcc, s18, v59
	v_cmp_gt_i32_e64 s[8:9], s2, v57
	v_or_b32_e32 v56, 3, v56
	s_and_b64 s[26:27], s[8:9], vcc
	v_cmp_lt_i32_e64 s[8:9], s28, v57
	v_sub_u32_e32 v57, v61, v56
	v_cmp_gt_u32_e32 vcc, s18, v57
	v_cmp_gt_i32_e64 s[10:11], s2, v56
	s_and_b64 s[66:67], s[10:11], vcc
	v_cmp_lt_i32_e64 s[10:11], s28, v56
	v_or_b32_e32 v56, v74, v60
	v_sub_u32_e32 v57, v61, v56
	v_cmp_gt_u32_e32 vcc, s18, v57
	v_or_b32_e32 v57, 1, v56
	v_cmp_gt_i32_e64 s[12:13], s2, v56
	v_sub_u32_e32 v59, v61, v57
	v_cmp_gt_i32_e64 s[14:15], s2, v57
	v_or_b32_e32 v57, 2, v56
	s_and_b64 s[48:49], s[12:13], vcc
	v_cmp_gt_u32_e32 vcc, s18, v59
	v_sub_u32_e32 v59, v61, v57
	v_cmp_lt_i32_e64 s[12:13], s28, v56
	s_and_b64 s[68:69], s[14:15], vcc
	v_cmp_lt_i32_e64 s[14:15], s16, v56
	v_cmp_gt_u32_e32 vcc, s18, v59
	v_cmp_gt_i32_e64 s[16:17], s2, v57
	v_or_b32_e32 v56, 3, v56
	s_and_b64 s[38:39], s[16:17], vcc
	v_cmp_lt_i32_e64 s[16:17], s28, v57
	v_sub_u32_e32 v57, v61, v56
	v_cmp_gt_u32_e32 vcc, s18, v57
	v_cmp_gt_i32_e64 s[18:19], s2, v56
	s_and_b64 s[70:71], s[18:19], vcc
	v_cmp_lt_i32_e64 s[18:19], s28, v56
	v_add_u32_e32 v56, 0x9900, v35
	v_add3_u32 v108, v56, v37, v36
	v_lshlrev_b32_e32 v37, 5, v58
	v_add3_u32 v109, v56, v55, v36
	v_lshlrev_b32_e32 v55, 5, v63
	v_add3_u32 v111, v35, v37, v36
	v_add3_u32 v112, v56, v37, v36
	v_lshlrev_b32_e32 v37, 5, v65
	v_add3_u32 v110, v35, v55, v36
	v_add3_u32 v113, v56, v55, v36
	v_lshlrev_b32_e32 v55, 5, v67
	v_add3_u32 v115, v35, v37, v36
	v_add3_u32 v116, v56, v37, v36
	v_lshlrev_b32_e32 v37, 5, v69
	v_add3_u32 v114, v35, v55, v36
	v_add3_u32 v117, v56, v55, v36
	v_lshlrev_b32_e32 v55, 5, v71
	v_add3_u32 v119, v35, v37, v36
	v_add3_u32 v120, v56, v37, v36
	v_lshlrev_b32_e32 v37, 5, v73
	v_add3_u32 v118, v35, v55, v36
	v_add3_u32 v121, v56, v55, v36
	v_add3_u32 v122, v35, v37, v36
	v_add3_u32 v123, v56, v37, v36
	v_and_b32_e32 v131, 7, v201
	v_bfe_u32 v106, v201, 3, 3
	v_lshrrev_b32_e32 v107, 6, v201
	v_lshrrev_b32_e32 v108, 2, v131
	v_and_b32_e32 v109, 3, v131
	v_lshlrev_b32_e32 v110, 5, v106
	v_lshl_add_u32 v110, v109, 3, v110
	v_lshl_add_u32 v110, v108, 6, v110
	v_and_b32_e32 v110, 0xff, v110
	v_lshl_add_u32 v110, v108, 9, v110
	v_lshl_add_u32 v128, v107, 10, v110
	v_and_b32_e32 v111, 63, v201
	v_and_b32_e32 v112, 15, v111
	v_lshrrev_b32_e32 v113, 4, v111
	v_and_b32_e32 v114, 1, v113
	v_lshrrev_b32_e32 v115, 1, v113
	v_lshrrev_b32_e32 v116, 2, v112
	v_and_b32_e32 v117, 3, v112
	v_lshl_add_u32 v116, v114, 2, v116
	v_lshlrev_b32_e32 v116, 5, v116
	v_lshl_add_u32 v116, v117, 3, v116
	v_lshlrev_b32_e32 v118, 11, v107
	v_lshl_add_u32 v118, v115, 10, v118
	v_add_u32_e32 v129, v118, v116
	v_add_u32_e32 v116, 64, v116
	v_and_b32_e32 v116, 0xff, v116
	v_add_u32_e32 v130, v118, v116
	v_add_u32_e32 v130, 0x200, v130
	s_waitcnt vmcnt(0)
	v_mov_b64_e32 v[34:35], v[46:47]
	v_mov_b64_e32 v[36:37], v[48:49]
	s_branch .LBB0_488

.LBB0_488:
	v_readlane_b32 s28, v251, 1
	s_add_i32 s30, s31, s28
	s_waitcnt lgkmcnt(0)
	s_barrier
	s_cmpk_gt_i32 s30, 0xbff
	s_cselect_b64 s[50:51], -1, 0
	s_and_b64 vcc, exec, s[50:51]
	ds_write_b128 v124, v[2:5]
	ds_write_b128 v125, v[6:9]
	ds_write_b128 v126, v[10:13]
	ds_write_b128 v127, v[14:17]
	ds_write_b64 v128, v[18:19] offset:39168
	ds_write_b64 v128, v[20:21] offset:39424
	ds_write_b64 v128, v[22:23] offset:47360
	ds_write_b64 v128, v[24:25] offset:47616
	ds_write_b64 v128, v[26:27] offset:55552
	ds_write_b64 v128, v[28:29] offset:55808
	ds_write_b64 v128, v[30:31] offset:63744
	ds_write_b64 v128, v[32:33] offset:64000
	v_readlane_b32 s29, v251, 2
	s_cbranch_vccnz .LBB0_506
	s_mul_hi_i32 s2, s30, 0x2aaaaaab
	s_lshr_b32 s28, s2, 31
	s_ashr_i32 s2, s2, 5
	s_add_i32 s2, s2, s28
	s_mul_i32 s28, s2, 0xffffff40
	s_add_i32 s28, s30, s28
	s_and_b32 s29, s28, 63
	s_ashr_i32 s28, s28, 5
	s_and_b32 s33, s28, -2
	s_lshr_b32 s28, 64, s33
	s_add_i32 s28, s28, -1
	s_sub_i32 s35, 6, s33
	s_and_b32 s28, s28, s29
	s_lshr_b32 s36, s29, s35
	s_lshl_b32 s35, s28, 7
	s_ashr_i32 s34, s2, 2
	s_add_i32 s73, s35, 0xffffff80
	s_lshl_b32 s28, s34, 13
	s_lshl_b32 s2, s2, 6
	v_add_u32_e32 v6, s73, v90
	v_mov_b32 v4, 0
	s_or_b32 s72, s36, s28
	v_mov_b32_e32 v5, v4
	s_and_b32 s37, s2, 0xc0
	v_cmp_lt_i32_e32 vcc, -1, v6
	v_mov_b64_e32 v[2:3], v[4:5]
	v_mov_b64_e32 v[18:19], v[4:5]
	v_mov_b64_e32 v[20:21], v[4:5]
	s_and_saveexec_b64 s[28:29], vcc
	s_cbranch_execz .LBB0_491
	v_readlane_b32 vcc_lo, v254, 1
	v_lshlrev_b32_e32 v2, s33, v6
	v_readlane_b32 vcc_hi, v254, 2
	v_add_u32_e32 v4, s72, v2
	s_movk_i32 s2, 0x1400
	v_mov_b64_e32 v[2:3], vcc
	v_mad_i64_i32 v[2:3], vcc, v4, s2, v[2:3]
	s_lshl_b32 s2, s37, 1
	v_lshl_add_u64 v[2:3], v[2:3], 0, s[2:3]
	v_mov_b32_e32 v79, v1
	v_lshl_add_u64 v[2:3], v[2:3], 0, v[78:79]
	global_load_dwordx4 v[18:21], v[2:3], off offset:1536
	s_nop 0
	global_load_dwordx4 v[2:5], v[2:3], off offset:1024
.LBB0_491:
	s_or_b64 exec, exec, s[28:29]
	v_add_u32_e32 v10, s73, v91
	v_mov_b32 v8, 0
	v_cmp_lt_i32_e32 vcc, -1, v10
	v_mov_b32_e32 v9, v8
	v_mov_b64_e32 v[6:7], v[8:9]
	v_mov_b64_e32 v[22:23], v[8:9]
	v_mov_b64_e32 v[24:25], v[8:9]
	s_and_saveexec_b64 s[28:29], vcc
	s_cbranch_execz .LBB0_493
	v_readlane_b32 vcc_lo, v254, 1
	v_lshlrev_b32_e32 v6, s33, v10
	v_readlane_b32 vcc_hi, v254, 2
	v_add_u32_e32 v8, s72, v6
	s_movk_i32 s2, 0x1400
	v_mov_b64_e32 v[6:7], vcc
	v_mad_i64_i32 v[6:7], vcc, v8, s2, v[6:7]
	s_lshl_b32 s2, s37, 1
	v_lshl_add_u64 v[6:7], v[6:7], 0, s[2:3]
	v_mov_b32_e32 v79, v1
	v_lshl_add_u64 v[6:7], v[6:7], 0, v[78:79]
	global_load_dwordx4 v[22:25], v[6:7], off offset:1536
	s_nop 0
	global_load_dwordx4 v[6:9], v[6:7], off offset:1024
.LBB0_493:
	s_or_b64 exec, exec, s[28:29]
	v_add_u32_e32 v14, s73, v92
	v_mov_b32 v12, 0
	v_cmp_lt_i32_e32 vcc, -1, v14
	v_mov_b32_e32 v13, v12
	v_mov_b64_e32 v[10:11], v[12:13]
	v_mov_b64_e32 v[26:27], v[12:13]
	v_mov_b64_e32 v[28:29], v[12:13]
	s_and_saveexec_b64 s[28:29], vcc
	s_cbranch_execz .LBB0_495
	v_readlane_b32 vcc_lo, v254, 1
	v_lshlrev_b32_e32 v10, s33, v14
	v_readlane_b32 vcc_hi, v254, 2
	v_add_u32_e32 v12, s72, v10
	s_movk_i32 s2, 0x1400
	v_mov_b64_e32 v[10:11], vcc
	v_mad_i64_i32 v[10:11], vcc, v12, s2, v[10:11]
	s_lshl_b32 s2, s37, 1
	v_lshl_add_u64 v[10:11], v[10:11], 0, s[2:3]
	v_mov_b32_e32 v79, v1
	v_lshl_add_u64 v[10:11], v[10:11], 0, v[78:79]
	global_load_dwordx4 v[26:29], v[10:11], off offset:1536
	s_nop 0
	global_load_dwordx4 v[10:13], v[10:11], off offset:1024
.LBB0_495:
	s_or_b64 exec, exec, s[28:29]
	v_add_u32_e32 v106, s73, v93
	v_mov_b32 v16, 0
	v_cmp_lt_i32_e32 vcc, -1, v106
	v_mov_b32_e32 v17, v16
	v_mov_b64_e32 v[14:15], v[16:17]
	v_mov_b64_e32 v[30:31], v[16:17]
	v_mov_b64_e32 v[32:33], v[16:17]
	s_and_saveexec_b64 s[28:29], vcc
	s_cbranch_execz .LBB0_497
	v_readlane_b32 vcc_lo, v254, 1
	v_lshlrev_b32_e32 v14, s33, v106
	v_readlane_b32 vcc_hi, v254, 2
	v_add_u32_e32 v16, s72, v14
	s_movk_i32 s2, 0x1400
	v_mov_b64_e32 v[14:15], vcc
	v_mad_i64_i32 v[14:15], vcc, v16, s2, v[14:15]
	s_lshl_b32 s2, s37, 1
	v_lshl_add_u64 v[14:15], v[14:15], 0, s[2:3]
	v_mov_b32_e32 v79, v1
	v_lshl_add_u64 v[14:15], v[14:15], 0, v[78:79]
	global_load_dwordx4 v[30:33], v[14:15], off offset:1536
	s_nop 0
	global_load_dwordx4 v[14:17], v[14:15], off offset:1024
.LBB0_497:
	s_or_b64 exec, exec, s[28:29]
	s_lshl_b32 s2, s37, 1
	v_add_u32_e32 v34, s35, v95
	s_ashr_i32 s35, s34, 31
	s_lshl_b64 s[28:29], s[34:35], 13
	v_ashrrev_i32_e32 v35, 31, v34
	v_lshlrev_b64 v[34:35], s33, v[34:35]
	s_or_b32 s28, s28, s36
	v_lshl_add_u64 v[34:35], s[28:29], 0, v[34:35]
	v_readlane_b32 s28, v254, 1
	v_readlane_b32 s29, v254, 2
	s_movk_i32 s33, 0x1400
	s_nop 0
	v_mov_b64_e32 v[36:37], s[28:29]
	v_mad_u64_u32 v[36:37], s[28:29], v34, s33, v[36:37]
	v_mov_b32_e32 v34, v37
	v_mad_u64_u32 v[34:35], s[28:29], v35, s33, v[34:35]
	v_mov_b32_e32 v37, v34
	v_lshl_add_u64 v[34:35], v[36:37], 0, s[2:3]
	v_lshl_add_u64 v[38:39], v[34:35], 0, v[0:1]
	global_load_dwordx4 v[34:37], v[38:39], off offset:512
	s_nop 0
	global_load_dwordx4 v[38:41], v[38:39], off offset:576
.LBB0_506:
	s_waitcnt lgkmcnt(0)
	s_barrier
	ds_read_b128 v[50:53], v97
	ds_read_b128 v[54:57], v97 offset:64
	s_mul_hi_i32 s2, s31, 0x2aaaaaab
	s_waitcnt lgkmcnt(1)
	v_mfma_f32_16x16x32_bf16 v[50:53], v[50:53], v[46:49], 0
	s_lshr_b32 s28, s2, 31
	s_ashr_i32 s2, s2, 5
	s_add_i32 s2, s2, s28
	s_waitcnt lgkmcnt(0)
	v_mfma_f32_16x16x32_bf16 v[132:135], v[54:57], v[42:45], v[50:53]
	s_nop 2
	ds_read_b128 v[50:53], v98
	ds_read_b128 v[54:57], v98 offset:64
	s_mul_i32 s28, s2, 0xffffff40
	s_add_i32 s29, s31, s28
	s_waitcnt lgkmcnt(1)
	v_mfma_f32_16x16x32_bf16 v[50:53], v[50:53], v[46:49], 0
	s_ashr_i32 s72, s29, 6
	s_lshl_b32 s33, s72, 1
	s_lshr_b32 s31, 64, s33
	s_waitcnt lgkmcnt(0)
	v_mfma_f32_16x16x32_bf16 v[74:77], v[54:57], v[42:45], v[50:53]
	s_nop 2
	ds_read_b128 v[50:53], v99
	ds_read_b128 v[54:57], v99 offset:64
	s_ashr_i32 s28, s2, 2
	s_sub_i32 s34, 6, s33
	s_waitcnt lgkmcnt(1)
	v_mfma_f32_16x16x32_bf16 v[50:53], v[50:53], v[46:49], 0
	s_add_i32 s35, s31, -1
	s_and_b32 s29, s29, 63
	s_lshr_b32 s36, s29, s34
	s_waitcnt lgkmcnt(0)
	v_mfma_f32_16x16x32_bf16 v[70:73], v[54:57], v[42:45], v[50:53]
	s_nop 2
	ds_read_b128 v[50:53], v100
	ds_read_b128 v[54:57], v100 offset:64
	s_and_b32 s31, s2, 3
	s_and_b32 s2, s35, s29
	s_waitcnt lgkmcnt(1)
	v_mfma_f32_16x16x32_bf16 v[50:53], v[50:53], v[46:49], 0
	s_ashr_i32 s29, s28, 31
	s_lshl_b64 s[34:35], s[28:29], 13
	s_or_b32 s34, s34, s36
	s_waitcnt lgkmcnt(0)
	v_mfma_f32_16x16x32_bf16 v[66:69], v[54:57], v[42:45], v[50:53]
	s_nop 2
	ds_read_b128 v[50:53], v101
	ds_read_b128 v[54:57], v101 offset:64
	s_cmp_lg_u32 s2, 0
	v_readlane_b32 s28, v253, 59
	s_waitcnt lgkmcnt(1)
	v_mfma_f32_16x16x32_bf16 v[50:53], v[50:53], v[46:49], 0
	s_cselect_b64 s[36:37], -1, 0
	v_readlane_b32 s29, v253, 60
	v_readlane_b32 vcc_lo, v254, 9
	s_waitcnt lgkmcnt(0)
	v_mfma_f32_16x16x32_bf16 v[62:65], v[54:57], v[42:45], v[50:53]
	s_nop 2
	ds_read_b128 v[50:53], v102
	ds_read_b128 v[54:57], v102 offset:64
	s_or_b64 s[28:29], s[28:29], s[36:37]
	v_readlane_b32 vcc_hi, v254, 10
	s_waitcnt lgkmcnt(1)
	v_mfma_f32_16x16x32_bf16 v[50:53], v[50:53], v[46:49], 0
	s_and_b64 vcc, vcc, s[28:29]
	v_readlane_b32 s28, v254, 22
	v_readlane_b32 s29, v254, 23
	s_waitcnt lgkmcnt(0)
	v_mfma_f32_16x16x32_bf16 v[58:61], v[54:57], v[42:45], v[50:53]
	s_nop 2
	ds_read_b128 v[50:53], v103
	ds_read_b128 v[54:57], v103 offset:64
	s_or_b64 s[28:29], s[28:29], s[36:37]
	s_ashr_i32 s73, s72, 31
	s_waitcnt lgkmcnt(1)
	v_mfma_f32_16x16x32_bf16 v[50:53], v[50:53], v[46:49], 0
	s_waitcnt lgkmcnt(0)
	v_mfma_f32_16x16x32_bf16 v[54:57], v[54:57], v[42:45], v[50:53]
	s_nop 5
	ds_read_b128 v[50:53], v104
	ds_read_b128 v[136:139], v104 offset:64
	s_waitcnt lgkmcnt(1)
	v_mfma_f32_16x16x32_bf16 v[50:53], v[50:53], v[46:49], 0
	s_waitcnt lgkmcnt(0)
	v_mfma_f32_16x16x32_bf16 v[50:53], v[136:139], v[42:45], v[50:53]
	ds_read_b128 v[136:139], v105
	ds_read_b128 v[140:143], v105 offset:64
	s_waitcnt lgkmcnt(1)
	v_mfma_f32_16x16x32_bf16 v[46:49], v[136:139], v[46:49], 0
	s_waitcnt lgkmcnt(0)
	v_mfma_f32_16x16x32_bf16 v[42:45], v[140:143], v[42:45], v[46:49]
	s_nop 5
	v_cndmask_b32_e32 v48, v244, v132, vcc
	v_readlane_b32 vcc_lo, v254, 20
	v_readlane_b32 vcc_hi, v254, 21
	s_and_b64 vcc, vcc, s[28:29]
	v_readlane_b32 s28, v254, 28
	v_cndmask_b32_e32 v49, v244, v133, vcc
	v_readlane_b32 s29, v254, 29
	v_readlane_b32 vcc_lo, v254, 26
	s_or_b64 s[28:29], s[28:29], s[36:37]
	v_readlane_b32 vcc_hi, v254, 27
	s_and_b64 vcc, vcc, s[28:29]
	v_readlane_b32 s28, v254, 32
	v_cndmask_b32_e32 v89, v244, v134, vcc
	v_readlane_b32 s29, v254, 33
	v_readlane_b32 vcc_lo, v254, 30
	s_or_b64 s[28:29], s[28:29], s[36:37]
	v_readlane_b32 vcc_hi, v254, 31
	s_and_b64 vcc, vcc, s[28:29]
	v_readlane_b32 s28, v254, 36
	v_cndmask_b32_e32 v132, v244, v135, vcc
	v_readlane_b32 s29, v254, 37
	v_readlane_b32 vcc_lo, v254, 34
	s_or_b64 s[28:29], s[28:29], s[36:37]
	v_readlane_b32 vcc_hi, v254, 35
	s_and_b64 vcc, vcc, s[28:29]
	v_readlane_b32 s28, v254, 40
	v_cndmask_b32_e32 v74, v244, v74, vcc
	v_readlane_b32 s29, v254, 41
	v_readlane_b32 vcc_lo, v254, 38
	s_or_b64 s[28:29], s[28:29], s[36:37]
	v_readlane_b32 vcc_hi, v254, 39
	s_and_b64 vcc, vcc, s[28:29]
	v_readlane_b32 s28, v254, 44
	v_cndmask_b32_e32 v75, v244, v75, vcc
	v_readlane_b32 s29, v254, 45
	v_readlane_b32 vcc_lo, v254, 42
	s_or_b64 s[28:29], s[28:29], s[36:37]
	v_readlane_b32 vcc_hi, v254, 43
	s_and_b64 vcc, vcc, s[28:29]
	v_readlane_b32 s28, v254, 48
	v_cndmask_b32_e32 v76, v244, v76, vcc
	v_readlane_b32 s29, v254, 49
	v_readlane_b32 vcc_lo, v254, 46
	s_or_b64 s[28:29], s[28:29], s[36:37]
	v_readlane_b32 vcc_hi, v254, 47
	s_and_b64 vcc, vcc, s[28:29]
	v_readlane_b32 s28, v254, 52
	v_cndmask_b32_e32 v77, v244, v77, vcc
	v_readlane_b32 s29, v254, 53
	v_readlane_b32 vcc_lo, v254, 50
	s_or_b64 s[28:29], s[28:29], s[36:37]
	v_readlane_b32 vcc_hi, v254, 51
	s_and_b64 vcc, vcc, s[28:29]
	v_readlane_b32 s28, v254, 56
	v_cndmask_b32_e32 v70, v244, v70, vcc
	v_readlane_b32 s29, v254, 57
	v_readlane_b32 vcc_lo, v254, 54
	s_or_b64 s[28:29], s[28:29], s[36:37]
	v_readlane_b32 vcc_hi, v254, 55
	s_and_b64 vcc, vcc, s[28:29]
	v_readlane_b32 s28, v254, 60
	v_cndmask_b32_e32 v71, v244, v71, vcc
	v_readlane_b32 s29, v254, 61
	v_readlane_b32 vcc_lo, v254, 58
	s_or_b64 s[28:29], s[28:29], s[36:37]
	v_readlane_b32 vcc_hi, v254, 59
	s_and_b64 vcc, vcc, s[28:29]
	v_readlane_b32 s28, v255, 0
	v_cndmask_b32_e32 v72, v244, v72, vcc
	v_readlane_b32 s29, v255, 1
	v_readlane_b32 vcc_lo, v254, 62
	s_or_b64 s[28:29], s[28:29], s[36:37]
	v_readlane_b32 vcc_hi, v254, 63
	s_and_b64 vcc, vcc, s[28:29]
	v_readlane_b32 s28, v255, 4
	v_cndmask_b32_e32 v73, v244, v73, vcc
	v_readlane_b32 s29, v255, 5
	v_readlane_b32 vcc_lo, v255, 2
	s_or_b64 s[28:29], s[28:29], s[36:37]
	v_readlane_b32 vcc_hi, v255, 3
	s_and_b64 vcc, vcc, s[28:29]
	v_readlane_b32 s28, v255, 8
	v_cndmask_b32_e32 v66, v244, v66, vcc
	v_readlane_b32 s29, v255, 9
	v_readlane_b32 vcc_lo, v255, 6
	s_or_b64 s[28:29], s[28:29], s[36:37]
	v_readlane_b32 vcc_hi, v255, 7
	s_and_b64 vcc, vcc, s[28:29]
	v_readlane_b32 s28, v255, 12
	v_cndmask_b32_e32 v67, v244, v67, vcc
	v_readlane_b32 s29, v255, 13
	v_readlane_b32 vcc_lo, v255, 10
	s_or_b64 s[28:29], s[28:29], s[36:37]
	v_readlane_b32 vcc_hi, v255, 11
	s_and_b64 vcc, vcc, s[28:29]
	v_readlane_b32 s28, v255, 16
	v_cndmask_b32_e32 v137, v244, v68, vcc
	v_readlane_b32 s29, v255, 17
	v_readlane_b32 vcc_lo, v255, 14
	s_or_b64 s[28:29], s[28:29], s[36:37]
	v_readlane_b32 vcc_hi, v255, 15
	s_and_b64 vcc, vcc, s[28:29]
	s_or_b64 s[28:29], s[74:75], s[36:37]
	v_cndmask_b32_e32 v69, v244, v69, vcc
	s_and_b64 vcc, s[40:41], s[28:29]
	s_or_b64 s[28:29], s[76:77], s[36:37]
	v_cndmask_b32_e32 v62, v244, v62, vcc
	s_and_b64 vcc, s[52:53], s[28:29]
	s_or_b64 s[28:29], s[78:79], s[36:37]
	v_cndmask_b32_e32 v63, v244, v63, vcc
	s_and_b64 vcc, s[20:21], s[28:29]
	s_or_b64 s[28:29], s[80:81], s[36:37]
	v_cndmask_b32_e32 v138, v244, v64, vcc
	s_and_b64 vcc, s[54:55], s[28:29]
	s_or_b64 s[28:29], s[82:83], s[36:37]
	v_cndmask_b32_e32 v65, v244, v65, vcc
	s_and_b64 vcc, s[42:43], s[28:29]
	s_or_b64 s[28:29], s[84:85], s[36:37]
	v_lshl_add_u32 v46, s2, 7, v96
	s_mov_b32 s2, 0xff800000
	v_cndmask_b32_e32 v58, v244, v58, vcc
	s_and_b64 vcc, s[56:57], s[28:29]
	s_or_b64 s[28:29], s[86:87], s[36:37]
	v_max3_f32 v79, v48, s2, v49
	v_cndmask_b32_e32 v59, v244, v59, vcc
	s_and_b64 vcc, s[22:23], s[28:29]
	s_or_b64 s[28:29], s[88:89], s[36:37]
	v_max3_f32 v79, v79, v89, v132
	v_cndmask_b32_e32 v139, v244, v60, vcc
	s_and_b64 vcc, s[58:59], s[28:29]
	s_or_b64 s[28:29], s[90:91], s[36:37]
	v_max3_f32 v79, v79, v74, v75
	v_cndmask_b32_e32 v61, v244, v61, vcc
	s_and_b64 vcc, s[44:45], s[28:29]
	s_or_b64 s[28:29], s[92:93], s[36:37]
	v_max3_f32 v79, v79, v76, v77
	v_cndmask_b32_e32 v54, v244, v54, vcc
	s_and_b64 vcc, s[60:61], s[28:29]
	s_or_b64 s[28:29], s[94:95], s[36:37]
	v_max3_f32 v79, v79, v70, v71
	v_cndmask_b32_e32 v55, v244, v55, vcc
	s_and_b64 vcc, s[24:25], s[28:29]
	s_or_b64 s[28:29], s[96:97], s[36:37]
	v_max3_f32 v79, v79, v72, v73
	v_cndmask_b32_e32 v56, v244, v56, vcc
	s_and_b64 vcc, s[62:63], s[28:29]
	s_or_b64 s[28:29], s[4:5], s[36:37]
	v_max3_f32 v79, v79, v66, v67
	v_cndmask_b32_e32 v57, v244, v57, vcc
	s_and_b64 vcc, s[46:47], s[28:29]
	s_or_b64 s[28:29], s[6:7], s[36:37]
	v_max3_f32 v68, v79, v137, v69
	v_cndmask_b32_e32 v50, v244, v50, vcc
	s_and_b64 vcc, s[64:65], s[28:29]
	s_or_b64 s[28:29], s[8:9], s[36:37]
	v_max3_f32 v68, v68, v62, v63
	v_cndmask_b32_e32 v51, v244, v51, vcc
	s_and_b64 vcc, s[26:27], s[28:29]
	s_or_b64 s[28:29], s[10:11], s[36:37]
	v_max3_f32 v64, v68, v138, v65
	v_cndmask_b32_e32 v140, v244, v52, vcc
	s_and_b64 vcc, s[66:67], s[28:29]
	s_or_b64 s[28:29], s[12:13], s[36:37]
	v_max3_f32 v64, v64, v58, v59
	v_cndmask_b32_e32 v141, v244, v53, vcc
	s_and_b64 vcc, s[48:49], s[28:29]
	s_or_b64 s[28:29], s[14:15], s[36:37]
	v_max3_f32 v60, v64, v139, v61
	v_cndmask_b32_e32 v142, v244, v42, vcc
	s_and_b64 vcc, s[68:69], s[28:29]
	s_or_b64 s[28:29], s[16:17], s[36:37]
	v_max3_f32 v60, v60, v54, v55
	v_cndmask_b32_e32 v143, v244, v43, vcc
	s_and_b64 vcc, s[38:39], s[28:29]
	v_max3_f32 v60, v60, v56, v57
	v_cndmask_b32_e32 v144, v244, v44, vcc
	s_or_b64 s[28:29], s[18:19], s[36:37]
	v_and_b32_e32 v44, 64, v243
	v_max3_f32 v60, v60, v50, v51
	s_and_b64 vcc, s[70:71], s[28:29]
	v_xor_b32_e32 v43, 16, v243
	v_add_u32_e32 v44, 64, v44
	v_max3_f32 v52, v60, v140, v141
	v_cndmask_b32_e32 v145, v244, v45, vcc
	v_cmp_lt_i32_e32 vcc, v43, v44
	v_max3_f32 v42, v52, v142, v143
	v_max3_f32 v42, v42, v144, v145
	v_cndmask_b32_e32 v43, v243, v43, vcc
	v_lshlrev_b32_e32 v146, 2, v43
	ds_bpermute_b32 v43, v146, v42
	v_ashrrev_i32_e32 v47, 31, v46
	v_lshlrev_b64 v[46:47], s33, v[46:47]
	s_waitcnt lgkmcnt(0)
	v_max_f32_e32 v43, v43, v43
	v_max_f32_e32 v42, v42, v43
	v_xor_b32_e32 v43, 32, v243
	v_cmp_lt_i32_e32 vcc, v43, v44
	s_nop 1
	v_cndmask_b32_e32 v43, v243, v43, vcc
	v_lshlrev_b32_e32 v147, 2, v43
	ds_bpermute_b32 v43, v147, v42
	s_waitcnt lgkmcnt(0)
	v_max_f32_e32 v43, v43, v43
	v_max_f32_e32 v60, v42, v43
	v_sub_f32_e32 v43, v49, v60
	v_sub_f32_e32 v49, v74, v60
	v_mul_f32_e32 v49, 0x3fb8aa3b, v49
	v_exp_f32_e32 v133, v49
	v_sub_f32_e32 v49, v75, v60
	v_mul_f32_e32 v49, 0x3fb8aa3b, v49
	v_exp_f32_e32 v134, v49
	v_sub_f32_e32 v49, v76, v60
	v_mul_f32_e32 v49, 0x3fb8aa3b, v49
	v_exp_f32_e32 v135, v49
	v_sub_f32_e32 v49, v77, v60
	v_mul_f32_e32 v49, 0x3fb8aa3b, v49
	v_exp_f32_e32 v136, v49
	v_sub_f32_e32 v49, v70, v60
	v_mul_f32_e32 v49, 0x3fb8aa3b, v49
	v_exp_f32_e32 v68, v49
	v_sub_f32_e32 v49, v71, v60
	v_sub_f32_e32 v42, v48, v60
	v_mul_f32_e32 v49, 0x3fb8aa3b, v49
	v_mul_f32_e32 v42, 0x3fb8aa3b, v42
	v_exp_f32_e32 v70, v49
	v_sub_f32_e32 v49, v72, v60
	v_exp_f32_e32 v42, v42
	v_mul_f32_e32 v43, 0x3fb8aa3b, v43
	v_mul_f32_e32 v49, 0x3fb8aa3b, v49
	v_exp_f32_e32 v43, v43
	v_exp_f32_e32 v72, v49
	v_sub_f32_e32 v49, v73, v60
	v_mul_f32_e32 v49, 0x3fb8aa3b, v49
	v_exp_f32_e32 v74, v49
	v_sub_f32_e32 v49, v66, v60
	v_add_f32_e32 v44, 0, v42
	v_mul_f32_e32 v49, 0x3fb8aa3b, v49
	v_add_f32_e32 v45, v43, v44
	v_sub_f32_e32 v44, v89, v60
	v_exp_f32_e32 v76, v49
	v_sub_f32_e32 v49, v67, v60
	v_mul_f32_e32 v44, 0x3fb8aa3b, v44
	v_mul_f32_e32 v49, 0x3fb8aa3b, v49
	v_exp_f32_e32 v44, v44
	v_exp_f32_e32 v79, v49
	v_sub_f32_e32 v49, v137, v60
	v_mul_f32_e32 v49, 0x3fb8aa3b, v49
	v_exp_f32_e32 v89, v49
	v_sub_f32_e32 v49, v69, v60
	v_mul_f32_e32 v49, 0x3fb8aa3b, v49
	v_add_f32_e32 v48, v44, v45
	v_sub_f32_e32 v45, v132, v60
	v_exp_f32_e32 v132, v49
	v_sub_f32_e32 v49, v62, v60
	v_mul_f32_e32 v49, 0x3fb8aa3b, v49
	v_exp_f32_e32 v64, v49
	v_sub_f32_e32 v49, v63, v60
	v_mul_f32_e32 v45, 0x3fb8aa3b, v45
	v_mul_f32_e32 v49, 0x3fb8aa3b, v49
	v_exp_f32_e32 v45, v45
	v_exp_f32_e32 v66, v49
	v_sub_f32_e32 v49, v138, v60
	v_mul_f32_e32 v49, 0x3fb8aa3b, v49
	v_exp_f32_e32 v67, v49
	v_sub_f32_e32 v49, v65, v60
	v_mul_f32_e32 v49, 0x3fb8aa3b, v49
	v_add_f32_e32 v48, v45, v48
	v_exp_f32_e32 v69, v49
	v_sub_f32_e32 v49, v58, v60
	v_add_f32_e32 v48, v133, v48
	v_mul_f32_e32 v49, 0x3fb8aa3b, v49
	v_add_f32_e32 v48, v134, v48
	v_exp_f32_e32 v71, v49
	v_sub_f32_e32 v49, v59, v60
	v_add_f32_e32 v48, v135, v48
	v_mul_f32_e32 v49, 0x3fb8aa3b, v49
	v_add_f32_e32 v48, v136, v48
	v_exp_f32_e32 v73, v49
	v_sub_f32_e32 v49, v139, v60
	v_add_f32_e32 v48, v68, v48
	v_mul_f32_e32 v49, 0x3fb8aa3b, v49
	v_add_f32_e32 v48, v70, v48
	v_exp_f32_e32 v75, v49
	v_sub_f32_e32 v49, v61, v60
	v_add_f32_e32 v48, v72, v48
	v_mul_f32_e32 v49, 0x3fb8aa3b, v49
	v_add_f32_e32 v48, v74, v48
	v_exp_f32_e32 v77, v49
	v_sub_f32_e32 v49, v54, v60
	v_add_f32_e32 v48, v76, v48
	v_mul_f32_e32 v49, 0x3fb8aa3b, v49
	v_add_f32_e32 v48, v79, v48
	v_exp_f32_e32 v52, v49
	v_sub_f32_e32 v49, v55, v60
	v_add_f32_e32 v48, v89, v48
	v_mul_f32_e32 v49, 0x3fb8aa3b, v49
	v_add_f32_e32 v48, v132, v48
	v_exp_f32_e32 v53, v49
	v_sub_f32_e32 v49, v56, v60
	v_add_f32_e32 v48, v64, v48
	v_mul_f32_e32 v49, 0x3fb8aa3b, v49
	v_add_f32_e32 v48, v66, v48
	v_exp_f32_e32 v54, v49
	v_sub_f32_e32 v49, v57, v60
	v_add_f32_e32 v48, v67, v48
	v_mul_f32_e32 v49, 0x3fb8aa3b, v49
	v_add_f32_e32 v48, v69, v48
	v_exp_f32_e32 v55, v49
	v_sub_f32_e32 v49, v50, v60
	v_add_f32_e32 v48, v71, v48
	v_mul_f32_e32 v49, 0x3fb8aa3b, v49
	v_add_f32_e32 v48, v73, v48
	v_exp_f32_e32 v56, v49
	v_sub_f32_e32 v49, v51, v60
	v_add_f32_e32 v48, v75, v48
	v_mul_f32_e32 v49, 0x3fb8aa3b, v49
	v_add_f32_e32 v48, v77, v48
	v_exp_f32_e32 v57, v49
	v_sub_f32_e32 v49, v140, v60
	v_add_f32_e32 v48, v52, v48
	v_mul_f32_e32 v49, 0x3fb8aa3b, v49
	v_add_f32_e32 v48, v53, v48
	v_exp_f32_e32 v63, v49
	v_sub_f32_e32 v49, v141, v60
	v_add_f32_e32 v48, v54, v48
	v_mul_f32_e32 v49, 0x3fb8aa3b, v49
	v_add_f32_e32 v48, v55, v48
	v_exp_f32_e32 v65, v49
	v_add_f32_e32 v48, v56, v48
	v_add_f32_e32 v48, v57, v48
	v_add_f32_e32 v48, v63, v48
	v_add_f32_e32 v49, v65, v48
	v_sub_f32_e32 v48, v142, v60
	v_mul_f32_e32 v48, 0x3fb8aa3b, v48
	v_exp_f32_e32 v48, v48
	v_cvt_pk_bf16_f32 v42, v42, v43
	v_cvt_pk_bf16_f32 v43, v44, v45
	v_cvt_pk_bf16_f32 v44, v133, v134
	v_cvt_pk_bf16_f32 v45, v135, v136
	ds_read_b64_tr_b16 v[136:137], v129 offset:41216
	ds_read_b64_tr_b16 v[134:135], v129 offset:39168
	v_add_f32_e32 v50, v48, v49
	v_sub_f32_e32 v49, v143, v60
	v_mul_f32_e32 v49, 0x3fb8aa3b, v49
	v_exp_f32_e32 v49, v49
	ds_read_b64_tr_b16 v[140:141], v129 offset:41472
	ds_read_b64_tr_b16 v[138:139], v129 offset:39424
	s_waitcnt lgkmcnt(2)
	v_mfma_f32_16x16x32_bf16 v[134:137], v[134:137], v[42:45], 0
	v_cvt_pk_bf16_f32 v67, v67, v69
	v_add_f32_e32 v51, v49, v50
	v_sub_f32_e32 v50, v144, v60
	v_mul_f32_e32 v50, 0x3fb8aa3b, v50
	v_exp_f32_e32 v50, v50
	s_waitcnt lgkmcnt(0)
	v_mfma_f32_16x16x32_bf16 v[138:141], v[138:141], v[42:45], 0
	v_cvt_pk_bf16_f32 v69, v75, v77
	v_cvt_pk_bf16_f32 v66, v64, v66
	v_add_f32_e32 v58, v50, v51
	v_sub_f32_e32 v51, v145, v60
	v_mul_f32_e32 v51, 0x3fb8aa3b, v51
	v_exp_f32_e32 v51, v51
	ds_read_b64_tr_b16 v[144:145], v130 offset:41216
	ds_read_b64_tr_b16 v[142:143], v130 offset:39168
	s_waitcnt lgkmcnt(0)
	v_mfma_f32_16x16x32_bf16 v[142:145], v[142:145], v[42:45], 0
	v_add_f32_e32 v58, v51, v58
	ds_bpermute_b32 v59, v146, v58
	v_cvt_pk_bf16_f32 v52, v52, v53
	v_cvt_pk_bf16_f32 v53, v54, v55
	v_cvt_pk_bf16_f32 v55, v63, v65
	v_cvt_pk_bf16_f32 v54, v56, v57
	s_waitcnt lgkmcnt(0)
	v_add_f32_e32 v61, v58, v59
	ds_bpermute_b32 v62, v147, v61
	ds_read_b64_tr_b16 v[146:147], v130 offset:39424
	ds_read_b64_tr_b16 v[148:149], v130 offset:41472
	ds_read_b64_tr_b16 v[152:153], v129 offset:45312
	ds_read_b64_tr_b16 v[150:151], v129 offset:43264
	s_waitcnt lgkmcnt(2)
	v_mfma_f32_16x16x32_bf16 v[42:45], v[146:149], v[42:45], 0
	v_cvt_pk_bf16_f32 v146, v68, v70
	v_cvt_pk_bf16_f32 v147, v72, v74
	v_cvt_pk_bf16_f32 v148, v76, v79
	v_cvt_pk_bf16_f32 v149, v89, v132
	v_cvt_pk_bf16_f32 v68, v71, v73
	v_lshl_add_u64 v[58:59], s[34:35], 0, v[46:47]
	s_waitcnt lgkmcnt(0)
	v_mfma_f32_16x16x32_bf16 v[132:135], v[150:153], v[146:149], v[134:137]
	ds_read_b64_tr_b16 v[152:153], v129 offset:45568
	ds_read_b64_tr_b16 v[150:151], v129 offset:43520
	v_add_f32_e32 v61, v61, v62
	v_div_scale_f32 v62, s[28:29], v61, v61, 1.0
	s_waitcnt lgkmcnt(0)
	v_mfma_f32_16x16x32_bf16 v[136:139], v[150:153], v[146:149], v[138:141]
	ds_read_b64_tr_b16 v[152:153], v130 offset:45312
	ds_read_b64_tr_b16 v[150:151], v130 offset:43264
	v_rcp_f32_e32 v63, v62
	s_lshl_b64 s[28:29], s[72:73], 24
	s_waitcnt lgkmcnt(0)
	v_mfma_f32_16x16x32_bf16 v[140:143], v[150:153], v[146:149], v[142:145]
	ds_read_b64_tr_b16 v[150:151], v130 offset:43520
	ds_read_b64_tr_b16 v[152:153], v130 offset:45568
	ds_read_b64_tr_b16 v[72:73], v129 offset:49408
	ds_read_b64_tr_b16 v[70:71], v129 offset:47360
	ds_read_b64_tr_b16 v[76:77], v129 offset:49664
	ds_read_b64_tr_b16 v[74:75], v129 offset:47616
	s_waitcnt lgkmcnt(2)
	v_mfma_f32_16x16x32_bf16 v[70:73], v[70:73], v[66:69], v[132:135]
	s_nop 2
	ds_read_b64_tr_b16 v[134:135], v130 offset:49408
	ds_read_b64_tr_b16 v[132:133], v130 offset:47360
	v_readlane_b32 s34, v254, 5
	v_readlane_b32 s35, v254, 6
	s_waitcnt lgkmcnt(2)
	v_mfma_f32_16x16x32_bf16 v[74:77], v[74:77], v[66:69], v[136:139]
	s_nop 2
	ds_read_b64_tr_b16 v[136:137], v130 offset:47616
	ds_read_b64_tr_b16 v[138:139], v130 offset:49664
	s_add_u32 s28, s34, s28
	s_addc_u32 s29, s35, s29
	v_mfma_f32_16x16x32_bf16 v[42:45], v[150:153], v[146:149], v[42:45]
	s_lshl_b32 s2, s31, 7
	v_mov_b32_e32 v89, v1
	s_waitcnt lgkmcnt(2)
	v_mfma_f32_16x16x32_bf16 v[132:135], v[132:135], v[66:69], v[140:143]
	s_waitcnt lgkmcnt(0)
	v_mfma_f32_16x16x32_bf16 v[42:45], v[136:139], v[66:69], v[42:45]
	ds_read_b64_tr_b16 v[66:67], v129 offset:53504
	ds_read_b64_tr_b16 v[64:65], v129 offset:51456
	s_waitcnt lgkmcnt(0)
	v_mfma_f32_16x16x32_bf16 v[64:67], v[64:67], v[52:55], v[70:73]
	s_nop 2
	ds_read_b64_tr_b16 v[70:71], v129 offset:53760
	ds_read_b64_tr_b16 v[68:69], v129 offset:51712
	s_waitcnt lgkmcnt(0)
	v_mfma_f32_16x16x32_bf16 v[68:71], v[68:71], v[52:55], v[74:77]
	s_nop 2
	ds_read_b64_tr_b16 v[74:75], v130 offset:53504
	ds_read_b64_tr_b16 v[72:73], v130 offset:51456
	s_waitcnt lgkmcnt(0)
	v_mfma_f32_16x16x32_bf16 v[72:75], v[72:75], v[52:55], v[132:135]
	s_nop 2
	ds_read_b64_tr_b16 v[132:133], v130 offset:51712
	ds_read_b64_tr_b16 v[134:135], v130 offset:53760
	ds_read_b64_tr_b16 v[46:47], v129 offset:55552
	s_waitcnt lgkmcnt(1)
	v_mfma_f32_16x16x32_bf16 v[42:45], v[132:135], v[52:55], v[42:45]
	v_cvt_pk_bf16_f32 v132, v48, v49
	v_mov_b32_e32 v48, v1
	v_mov_b32_e32 v49, v1
	v_mov_b32_e32 v134, v1
	v_mov_b32_e32 v135, v1
	v_cvt_pk_bf16_f32 v133, v50, v51
	s_waitcnt lgkmcnt(0)
	s_nop 0
	v_mfma_f32_16x16x32_bf16 v[54:57], v[46:49], v[132:135], v[64:67]
	ds_read_b64_tr_b16 v[46:47], v129 offset:55808
	s_nop 1
	ds_read_b64_tr_b16 v[64:65], v130 offset:55808
	v_mov_b32_e32 v66, v1
	v_mov_b32_e32 v67, v1
	s_waitcnt lgkmcnt(1)
	v_mfma_f32_16x16x32_bf16 v[50:53], v[46:49], v[132:135], v[68:71]
	ds_read_b64_tr_b16 v[46:47], v130 offset:55552
	s_waitcnt lgkmcnt(1)
	v_mfma_f32_16x16x32_bf16 v[42:45], v[64:67], v[132:135], v[42:45]
	v_fma_f32 v64, -v62, v63, 1.0
	v_fmac_f32_e32 v63, v64, v63
	v_div_scale_f32 v64, vcc, 1.0, v61, 1.0
	v_mul_f32_e32 v65, v64, v63
	v_fma_f32 v66, -v62, v65, v64
	v_fmac_f32_e32 v65, v66, v63
	s_waitcnt lgkmcnt(0)
	v_mfma_f32_16x16x32_bf16 v[46:49], v[46:49], v[132:135], v[72:75]
	v_fma_f32 v62, -v62, v65, v64
	v_div_fmas_f32 v62, v62, v63, v65
	v_div_fixup_f32 v64, v62, v61, 1.0
	v_lshlrev_b64 v[62:63], 9, v[58:59]
	v_lshl_add_u64 v[62:63], s[28:29], 0, v[62:63]
	v_lshl_add_u64 v[62:63], v[62:63], 0, s[2:3]
	v_mul_f32_e32 v54, v64, v54
	v_mul_f32_e32 v55, v64, v55
	v_mul_f32_e32 v46, v64, v46
	v_mul_f32_e32 v47, v64, v47
	v_lshl_add_u64 v[62:63], v[62:63], 0, v[88:89]
	v_cvt_pk_bf16_f32 v54, v54, v55
	v_mul_f32_e32 v55, v64, v56
	v_mul_f32_e32 v56, v64, v57
	v_mul_f32_e32 v50, v64, v50
	v_mul_f32_e32 v51, v64, v51
	v_cvt_pk_bf16_f32 v46, v46, v47
	v_mul_f32_e32 v47, v64, v48
	v_mul_f32_e32 v48, v64, v49
	v_mul_f32_e32 v42, v64, v42
	v_mul_f32_e32 v43, v64, v43
	v_cvt_pk_bf16_f32 v55, v55, v56
	v_cvt_pk_bf16_f32 v56, v50, v51
	v_mul_f32_e32 v50, v64, v52
	v_mul_f32_e32 v51, v64, v53
	v_cvt_pk_bf16_f32 v57, v50, v51
	global_store_dwordx4 v[62:63], v[54:57], off
	v_cvt_pk_bf16_f32 v47, v47, v48
	v_cvt_pk_bf16_f32 v48, v42, v43
	v_mul_f32_e32 v42, v64, v44
	v_mul_f32_e32 v43, v64, v45
	v_cvt_pk_bf16_f32 v49, v42, v43
	global_store_dwordx4 v[62:63], v[46:49], off offset:64
	s_mov_b64 s[28:29], exec
	v_readlane_b32 s34, v254, 24
	v_readlane_b32 s35, v254, 25
	s_and_b64 s[34:35], s[28:29], s[34:35]
	s_mov_b64 exec, s[34:35]
	s_cbranch_execz .LBB0_487
	s_mov_b32 s2, 0x800000
	v_cmp_gt_f32_e32 vcc, s2, v61
	s_mov_b32 s2, 0x3f317217
	s_lshl_b64 s[34:35], s[72:73], 19
	v_cndmask_b32_e64 v42, 0, 32, vcc
	v_ldexp_f32 v42, v61, v42
	v_log_f32_e32 v42, v42
	v_cndmask_b32_e32 v43, 0, v245, vcc
	v_readlane_b32 s36, v254, 7
	v_readlane_b32 s37, v254, 8
	v_mul_f32_e32 v44, 0x3f317217, v42
	v_fma_f32 v44, v42, s2, -v44
	v_fmac_f32_e32 v44, 0x3377d1cf, v42
	s_mov_b32 s2, 0x7f800000
	v_fmac_f32_e32 v44, 0x3f317217, v42
	v_cmp_lt_f32_e64 vcc, |v42|, s2
	s_add_u32 s34, s36, s34
	s_addc_u32 s35, s37, s35
	v_cndmask_b32_e32 v42, v42, v44, vcc
	v_sub_f32_e32 v42, v42, v43
	v_add_f32_e32 v44, v60, v42
	v_lshl_add_u64 v[42:43], v[58:59], 4, s[34:35]
	s_lshl_b32 s2, s31, 2
	v_lshl_add_u64 v[42:43], v[42:43], 0, s[2:3]
	global_store_dword v[42:43], v44, off
	s_branch .LBB0_487
	s_nop 0
	s_nop 0
	s_nop 0
